# v26 + decode page-table entries loaded once per task (no per-iteration drain)
# speedup vs baseline: 1.0192x; 1.0192x over previous
.LBB0_1241:
	s_or_b64 exec, exec, s[10:11]
	s_lshl_b32 s0, s13, 2
	s_and_b32 s0, s0, -16
	s_ashr_i32 s1, s0, 31
	s_lshl_b32 s14, s43, 7
	s_and_b32 s15, s42, 7
	s_lshl_b64 s[0:1], s[0:1], 2
	s_add_u32 s0, s60, s0
	s_addc_u32 s1, s61, s1
	s_lshl_b32 s10, s15, 3
	s_load_dwordx2 s[98:99], s[0:1], s10
	v_mov_b32_e32 v2, s10
	global_load_dword v4, v2, s[0:1]
	v_lshlrev_b32_e32 v5, 13, v139
	v_lshl_or_b32 v6, v123, 4, v5
	s_lshl_b32 s13, s14, 2
	v_lshlrev_b32_e32 v2, 5, v139
	v_mov_b32_e32 v7, v3
	v_lshl_add_u32 v2, v123, 11, v2
	s_lshl_b32 s10, s43, 9
	v_lshlrev_b32_e32 v124, 2, v139
	v_lshl_add_u64 v[128:129], s[56:57], 0, v[2:3]
	s_lshl_b32 s22, s15, 8
	s_add_i32 s43, s10, 0
	v_lshl_add_u64 v[130:131], s[58:59], 0, v[6:7]
	v_sub_u32_e32 v141, v125, v124
	s_add_i32 s43, s43, 0x26a00
	s_waitcnt vmcnt(4)
	v_subrev_u32_e32 v142, s22, v141
	s_mov_b32 s68, 0
	v_mov_b32_e32 v138, 0
	v_mov_b32_e32 v140, 0xf149f2ca
	s_mov_b32 s69, 16
	s_waitcnt vmcnt(0) lgkmcnt(0)
	v_ashrrev_i32_e32 v5, 31, v4
	v_lshlrev_b64 v[4:5], 18, v[4:5]
	v_or_b32_e32 v4, s13, v4
	v_lshl_add_u64 v[8:9], s[56:57], 0, v[4:5]
	v_lshl_add_u64 v[4:5], s[58:59], 0, v[4:5]
	v_lshl_add_u64 v[8:9], v[8:9], 0, v[2:3]
	v_lshl_add_u64 v[4:5], v[4:5], 0, v[6:7]
	v_lshl_add_u64 v[10:11], v[4:5], 0, s[38:39]
	global_load_dwordx4 v[52:55], v[8:9], off offset:16
	global_load_dwordx4 v[56:59], v[8:9], off
	global_load_dwordx4 v[60:63], v[8:9], off offset:144
	global_load_dwordx4 v[64:67], v[8:9], off offset:128
	global_load_dwordx4 v[68:71], v[8:9], off offset:272
	global_load_dwordx4 v[72:75], v[8:9], off offset:256
	global_load_dwordx4 v[76:79], v[8:9], off offset:400
	global_load_dwordx4 v[80:83], v[8:9], off offset:384
	global_load_dwordx4 v[84:87], v[4:5], off
	global_load_dwordx4 v[88:91], v[4:5], off offset:256
	global_load_dwordx4 v[92:95], v[4:5], off offset:2048
	global_load_dwordx4 v[96:99], v[4:5], off offset:2304
	global_load_dwordx4 v[100:103], v[10:11], off
	global_load_dwordx4 v[104:107], v[10:11], off offset:256
	global_load_dwordx4 v[108:111], v[10:11], off offset:2048
	global_load_dwordx4 v[112:115], v[10:11], off offset:2304
	v_mov_b32_e32 v4, v3
	v_mov_b32_e32 v5, v3
	v_mov_b32_e32 v2, v3
	v_mov_b64_e32 v[22:23], v[4:5]
	v_mov_b64_e32 v[30:31], v[4:5]
	v_mov_b64_e32 v[34:35], v[4:5]
	v_mov_b64_e32 v[26:27], v[4:5]
	v_mov_b64_e32 v[10:11], v[4:5]
	v_mov_b64_e32 v[14:15], v[4:5]
	v_mov_b64_e32 v[18:19], v[4:5]
	v_mov_b64_e32 v[20:21], v[2:3]
	v_mov_b64_e32 v[28:29], v[2:3]
	v_mov_b64_e32 v[32:33], v[2:3]
	v_mov_b64_e32 v[24:25], v[2:3]
	v_mov_b64_e32 v[8:9], v[2:3]
	v_mov_b64_e32 v[12:13], v[2:3]
	v_mov_b64_e32 v[16:17], v[2:3]
	v_mov_b64_e32 v[6:7], v[4:5]
	v_mov_b64_e32 v[4:5], v[2:3]
	s_branch .LBB0_1243
